# G1/G4 mainloop software-pipelined across the barrier (3 stages in flight, B frags double-buffered)
# speedup vs baseline: 1.0014x; 1.0014x over previous
.LBB1_54:
	v_readlane_b32 s4, v242, 0
	s_lshl_b32 s5, s2, 3
	s_and_b32 s6, s4, 7
	s_or_b32 s5, s6, s5
	s_mul_i32 s5, s5, s55
	s_ashr_i32 s4, s4, 3
	s_add_i32 s4, s5, s4
	s_cmpk_lt_i32 s4, 0x400
	s_mov_b64 s[40:41], -1
	s_cbranch_scc0 .LBB1_53
	s_ashr_i32 s5, s4, 31
	s_lshr_b32 s5, s5, 25
	s_add_i32 s5, s4, s5
	s_and_b32 s6, s5, 0xffffff80
	s_sub_i32 s7, s4, s6
	s_ashr_i32 s4, s7, 31
	s_lshr_b32 s4, s4, 29
	s_add_i32 s6, s7, s4
	s_and_b32 s4, s6, 0xfffff8
	s_sub_i32 s4, s7, s4
	s_lshl_b32 s5, s5, 4
	s_and_b32 s5, s5, 0xfffff800
	s_lshl_b32 s4, s4, 8
	s_add_i32 s4, s4, s5
	s_lshl_b32 s5, s6, 4
	v_mov_b32_e32 v134, v162
	s_and_b32 s40, s5, 0xffffff80
	s_movk_i32 s10, 0x78
	v_readfirstlane_b32 s5, v134
	v_lshrrev_b32_e32 v0, 3, v134
	v_and_b32_e32 v0, 6, v0
	s_and_b32 s8, s5, 0xffffffc0
	s_waitcnt lgkmcnt(0)
	v_bfe_u32 v2, v134, 2, 4
	v_lshrrev_b32_e64 v0, v0, s10
	s_add_i32 s8, s8, s4
	v_xor_b32_e32 v3, v0, v134
	v_or_b32_e32 v0, s8, v2
	v_ashrrev_i32_e32 v1, 31, v0
	v_lshlrev_b64 v[0:1], 11, v[0:1]
	v_lshlrev_b32_e32 v3, 4, v3
	v_lshl_add_u64 v[0:1], s[74:75], 0, v[0:1]
	v_and_b32_e32 v128, 48, v3
	s_load_dwordx16 s[80:95], s[0:1], 0xc0
	s_ashr_i32 s6, s5, 6
	v_lshl_add_u64 v[130:131], v[0:1], 0, v[128:129]
	v_or_b32_e32 v0, s40, v2
	v_lshl_add_u32 v0, s6, 5, v0
	v_ashrrev_i32_e32 v1, 31, v0
	v_lshlrev_b64 v[0:1], 11, v[0:1]
	s_waitcnt lgkmcnt(0)
	v_lshl_add_u64 v[0:1], s[92:93], 0, v[0:1]
	v_lshl_add_u64 v[132:133], v[0:1], 0, v[128:129]
	v_lshrrev_b32_e32 v0, 1, v134
	v_and_b32_e32 v0, 6, v0
	v_bfe_u32 v136, v134, 4, 2
	s_lshl_b32 s8, s6, 12
	v_lshrrev_b32_e64 v0, v0, s10
	v_and_b32_e32 v135, 15, v134
	s_lshl_b32 s9, s6, 11
	s_and_b32 s6, s5, 0xffffff80
	v_bitop3_b32 v0, v0, v136, 3 bitop3:0x6c
	s_and_b32 s5, s5, 64
	s_add_i32 s10, s8, 16
	v_lshlrev_b32_e32 v138, 4, v0
	v_or_b32_e32 v0, s5, v135
	s_mov_b32 m0, s10
	v_lshlrev_b32_e32 v139, 6, v0
	s_barrier
	global_load_lds_dwordx4 v[130:131], off
	v_lshl_add_u64 v[0:1], v[130:131], 0, s[34:35]
	s_add_i32 m0, s10, 0x400
	s_mov_b64 s[12:13], 0x10000
	global_load_lds_dwordx4 v[0:1], off
	v_lshl_add_u64 v[0:1], v[130:131], 0, s[12:13]
	s_add_i32 m0, s10, 0x800
	s_mov_b64 s[12:13], 0x18000
	global_load_lds_dwordx4 v[0:1], off
	v_lshl_add_u64 v[0:1], v[130:131], 0, s[12:13]
	s_add_i32 m0, s10, 0xc00
	s_sub_i32 s11, s10, s9
	global_load_lds_dwordx4 v[0:1], off
	s_add_i32 m0, s11, 0x4000
	v_lshl_add_u64 v[0:1], v[132:133], 0, s[34:35]
	global_load_lds_dwordx4 v[132:133], off
	s_add_i32 m0, s11, 0x4400
	s_mov_b64 s[12:13], 0x8040
	global_load_lds_dwordx4 v[0:1], off
	v_lshl_add_u64 v[0:1], v[130:131], 0, 64
	s_add_i32 m0, s10, 0x6000
	s_mov_b64 s[14:15], 0x10040
	global_load_lds_dwordx4 v[0:1], off
	v_lshl_add_u64 v[0:1], v[130:131], 0, s[12:13]
	s_add_i32 m0, s10, 0x6400
	v_or_b32_e32 v128, s6, v135
	global_load_lds_dwordx4 v[0:1], off
	v_lshl_add_u64 v[0:1], v[130:131], 0, s[14:15]
	s_add_i32 m0, s10, 0x6800
	s_mov_b64 s[14:15], 0x18040
	global_load_lds_dwordx4 v[0:1], off
	v_lshl_add_u64 v[0:1], v[130:131], 0, s[14:15]
	s_add_i32 m0, s10, 0x6c00
	v_lshlrev_b32_e32 v137, 6, v128
	global_load_lds_dwordx4 v[0:1], off
	v_lshl_add_u64 v[0:1], v[132:133], 0, 64
	s_add_i32 m0, s11, 0xa000
	s_mov_b32 s10, 0
	global_load_lds_dwordx4 v[0:1], off
	v_lshl_add_u64 v[0:1], v[132:133], 0, s[12:13]
	s_add_i32 m0, s11, 0xa400
	s_mov_b32 s11, 0
	global_load_lds_dwordx4 v[0:1], off
	v_mov_b32_e32 v0, 0
	v_mov_b32_e32 v1, v0
	v_mov_b32_e32 v2, v0
	v_mov_b32_e32 v3, v0
	v_mov_b32_e32 v4, v0
	v_mov_b32_e32 v5, v0
	v_mov_b32_e32 v6, v0
	v_mov_b32_e32 v7, v0
	v_mov_b32_e32 v8, v0
	v_mov_b32_e32 v9, v0
	v_mov_b32_e32 v10, v0
	v_mov_b32_e32 v11, v0
	v_mov_b32_e32 v12, v0
	v_mov_b32_e32 v13, v0
	v_mov_b32_e32 v14, v0
	v_mov_b32_e32 v15, v0
	v_mov_b32_e32 v16, v0
	v_mov_b32_e32 v17, v0
	v_mov_b32_e32 v18, v0
	v_mov_b32_e32 v19, v0
	v_mov_b32_e32 v20, v0
	v_mov_b32_e32 v21, v0
	v_mov_b32_e32 v22, v0
	v_mov_b32_e32 v23, v0
	v_mov_b32_e32 v24, v0
	v_mov_b32_e32 v25, v0
	v_mov_b32_e32 v26, v0
	v_mov_b32_e32 v27, v0
	v_mov_b32_e32 v28, v0
	v_mov_b32_e32 v29, v0
	v_mov_b32_e32 v30, v0
	v_mov_b32_e32 v31, v0
	v_mov_b32_e32 v32, v0
	v_mov_b32_e32 v33, v0
	v_mov_b32_e32 v34, v0
	v_mov_b32_e32 v35, v0
	v_mov_b32_e32 v36, v0
	v_mov_b32_e32 v37, v0
	v_mov_b32_e32 v38, v0
	v_mov_b32_e32 v39, v0
	v_mov_b32_e32 v40, v0
	v_mov_b32_e32 v41, v0
	v_mov_b32_e32 v42, v0
	v_mov_b32_e32 v43, v0
	v_mov_b32_e32 v44, v0
	v_mov_b32_e32 v45, v0
	v_mov_b32_e32 v46, v0
	v_mov_b32_e32 v47, v0
	v_mov_b32_e32 v48, v0
	v_mov_b32_e32 v49, v0
	v_mov_b32_e32 v50, v0
	v_mov_b32_e32 v51, v0
	v_mov_b32_e32 v52, v0
	v_mov_b32_e32 v53, v0
	v_mov_b32_e32 v54, v0
	v_mov_b32_e32 v55, v0
	v_mov_b32_e32 v56, v0
	v_mov_b32_e32 v57, v0
	v_mov_b32_e32 v58, v0
	v_mov_b32_e32 v59, v0
	v_mov_b32_e32 v60, v0
	v_mov_b32_e32 v61, v0
	v_mov_b32_e32 v62, v0
	v_mov_b32_e32 v63, v0
	v_mov_b32_e32 v64, v0
	v_mov_b32_e32 v65, v0
	v_mov_b32_e32 v66, v0
	v_mov_b32_e32 v67, v0
	v_mov_b32_e32 v68, v0
	v_mov_b32_e32 v69, v0
	v_mov_b32_e32 v70, v0
	v_mov_b32_e32 v71, v0
	v_mov_b32_e32 v72, v0
	v_mov_b32_e32 v73, v0
	v_mov_b32_e32 v74, v0
	v_mov_b32_e32 v75, v0
	v_mov_b32_e32 v84, v0
	v_mov_b32_e32 v85, v0
	v_mov_b32_e32 v86, v0
	v_mov_b32_e32 v87, v0
	v_mov_b32_e32 v96, v0
	v_mov_b32_e32 v97, v0
	v_mov_b32_e32 v98, v0
	v_mov_b32_e32 v99, v0
	v_mov_b32_e32 v100, v0
	v_mov_b32_e32 v101, v0
	v_mov_b32_e32 v102, v0
	v_mov_b32_e32 v103, v0
	v_mov_b32_e32 v104, v0
	v_mov_b32_e32 v105, v0
	v_mov_b32_e32 v106, v0
	v_mov_b32_e32 v107, v0
	v_mov_b32_e32 v108, v0
	v_mov_b32_e32 v109, v0
	v_mov_b32_e32 v110, v0
	v_mov_b32_e32 v111, v0
	v_mov_b32_e32 v112, v0
	v_mov_b32_e32 v113, v0
	v_mov_b32_e32 v114, v0
	v_mov_b32_e32 v115, v0
	v_mov_b32_e32 v116, v0
	v_mov_b32_e32 v117, v0
	v_mov_b32_e32 v118, v0
	v_mov_b32_e32 v119, v0
	v_mov_b32_e32 v120, v0
	v_mov_b32_e32 v121, v0
	v_mov_b32_e32 v122, v0
	v_mov_b32_e32 v123, v0
	v_mov_b32_e32 v124, v0
	v_mov_b32_e32 v125, v0
	v_mov_b32_e32 v126, v0
	v_mov_b32_e32 v127, v0
	v_mov_b32_e32 v76, v0
	v_mov_b32_e32 v77, v0
	v_mov_b32_e32 v78, v0
	v_mov_b32_e32 v79, v0
	v_mov_b32_e32 v80, v0
	v_mov_b32_e32 v81, v0
	v_mov_b32_e32 v82, v0
	v_mov_b32_e32 v83, v0
	v_mov_b32_e32 v88, v0
	v_mov_b32_e32 v89, v0
	v_mov_b32_e32 v90, v0
	v_mov_b32_e32 v91, v0
	v_mov_b32_e32 v92, v0
	v_mov_b32_e32 v93, v0
	v_mov_b32_e32 v94, v0
	v_mov_b32_e32 v95, v0
	s_mov_b64 s[16:17], 0x10080
	v_lshl_add_u64 v[196:197], v[130:131], 0, s[62:63]
	v_lshl_add_u64 v[198:199], v[130:131], 0, s[60:61]
	v_lshl_add_u64 v[200:201], v[130:131], 0, s[16:17]
	v_lshl_add_u64 v[202:203], v[130:131], 0, s[24:25]
	v_lshl_add_u64 v[204:205], v[132:133], 0, s[62:63]
	v_lshl_add_u64 v[206:207], v[132:133], 0, s[60:61]
	s_add_i32 s14, s8, 0xc010
	s_add_i32 s98, s9, 0x10010
	s_mov_b32 m0, s14
	s_nop 0
	global_load_lds_dwordx4 v[196:197], off
	s_add_i32 m0, s14, 0x400
	s_nop 0
	global_load_lds_dwordx4 v[198:199], off
	s_add_i32 m0, s14, 0x800
	s_nop 0
	global_load_lds_dwordx4 v[200:201], off
	s_add_i32 m0, s14, 0xc00
	s_nop 0
	global_load_lds_dwordx4 v[202:203], off
	s_mov_b32 m0, s98
	s_nop 0
	global_load_lds_dwordx4 v[204:205], off
	s_add_i32 m0, s98, 0x400
	s_nop 0
	global_load_lds_dwordx4 v[206:207], off
	s_waitcnt vmcnt(12)
	s_barrier
	v_add3_u32 v233, 16, v139, v138
	v_add3_u32 v232, 16, v137, v138
	ds_read_b128 v[140:143], v233 offset:16384
	ds_read_b128 v[144:147], v233 offset:17408
	ds_read_b128 v[148:151], v233 offset:18432
	ds_read_b128 v[152:155], v233 offset:19456
	ds_read_b128 v[156:159], v232
	ds_read_b128 v[188:191], v232 offset:1024
	ds_read_b128 v[192:195], v232 offset:2048
	s_setprio 1
.LBB1_56:
	s_mul_i32 s12, s10, 0x6000
	s_add_i32 s12, s12, 16
	s_add_i32 s13, s12, 0x6000
	s_cmp_eq_u32 s10, 2
	s_cselect_b32 s13, 16, s13
	s_min_u32 s14, s11, 28
	s_add_i32 s14, s14, 1
	s_lshl_b32 s96, s14, 6
	s_add_i32 s14, s12, s8
	s_add_i32 s98, s12, s9
	s_addk_i32 s98, 0x4000
	ds_read_b128 v[208:211], v232 offset:3072
	s_waitcnt lgkmcnt(3)
	v_mfma_f32_16x16x32_bf16 v[124:127], v[140:143], v[156:159], v[124:127]
	v_lshl_add_u64 v[234:235], v[130:131], 0, s[96:97]
	v_mfma_f32_16x16x32_bf16 v[120:123], v[144:147], v[156:159], v[120:123]
	v_lshl_add_u64 v[196:197], v[234:235], 0, s[62:63]
	v_mfma_f32_16x16x32_bf16 v[116:119], v[148:151], v[156:159], v[116:119]
	v_lshl_add_u64 v[198:199], v[234:235], 0, s[60:61]
	v_mfma_f32_16x16x32_bf16 v[112:115], v[152:155], v[156:159], v[112:115]
	ds_read_b128 v[156:159], v232 offset:4096
	s_waitcnt lgkmcnt(3)
	v_mfma_f32_16x16x32_bf16 v[108:111], v[140:143], v[188:191], v[108:111]
	v_lshl_add_u64 v[200:201], v[234:235], 0, s[16:17]
	v_mfma_f32_16x16x32_bf16 v[104:107], v[144:147], v[188:191], v[104:107]
	v_lshl_add_u64 v[202:203], v[234:235], 0, s[24:25]
	v_mfma_f32_16x16x32_bf16 v[100:103], v[148:151], v[188:191], v[100:103]
	v_lshl_add_u64 v[234:235], v[132:133], 0, s[96:97]
	v_mfma_f32_16x16x32_bf16 v[96:99], v[152:155], v[188:191], v[96:99]
	ds_read_b128 v[188:191], v232 offset:5120
	s_waitcnt lgkmcnt(3)
	v_mfma_f32_16x16x32_bf16 v[84:87], v[140:143], v[192:195], v[84:87]
	v_lshl_add_u64 v[204:205], v[234:235], 0, s[62:63]
	v_mfma_f32_16x16x32_bf16 v[72:75], v[144:147], v[192:195], v[72:75]
	v_lshl_add_u64 v[206:207], v[234:235], 0, s[60:61]
	v_mfma_f32_16x16x32_bf16 v[68:71], v[148:151], v[192:195], v[68:71]
	v_mfma_f32_16x16x32_bf16 v[64:67], v[152:155], v[192:195], v[64:67]
	ds_read_b128 v[192:195], v232 offset:6144
	s_waitcnt lgkmcnt(3)
	v_mfma_f32_16x16x32_bf16 v[60:63], v[140:143], v[208:211], v[60:63]
	v_mfma_f32_16x16x32_bf16 v[56:59], v[144:147], v[208:211], v[56:59]
	v_mfma_f32_16x16x32_bf16 v[52:55], v[148:151], v[208:211], v[52:55]
	v_mfma_f32_16x16x32_bf16 v[48:51], v[152:155], v[208:211], v[48:51]
	ds_read_b128 v[208:211], v232 offset:7168
	s_waitcnt lgkmcnt(3)
	v_mfma_f32_16x16x32_bf16 v[44:47], v[140:143], v[156:159], v[44:47]
	v_add3_u32 v232, s13, v137, v138
	v_mfma_f32_16x16x32_bf16 v[40:43], v[144:147], v[156:159], v[40:43]
	v_add3_u32 v233, s13, v139, v138
	v_mfma_f32_16x16x32_bf16 v[36:39], v[148:151], v[156:159], v[36:39]
	v_mfma_f32_16x16x32_bf16 v[32:35], v[152:155], v[156:159], v[32:35]
	s_waitcnt vmcnt(6)
	s_waitcnt lgkmcnt(0)
	s_barrier
	v_mfma_f32_16x16x32_bf16 v[28:31], v[140:143], v[188:191], v[28:31]
	ds_read_b128 v[216:219], v233 offset:16384
	v_mfma_f32_16x16x32_bf16 v[24:27], v[144:147], v[188:191], v[24:27]
	ds_read_b128 v[220:223], v233 offset:17408
	v_mfma_f32_16x16x32_bf16 v[20:23], v[148:151], v[188:191], v[20:23]
	ds_read_b128 v[224:227], v233 offset:18432
	v_mfma_f32_16x16x32_bf16 v[16:19], v[152:155], v[188:191], v[16:19]
	ds_read_b128 v[228:231], v233 offset:19456
	ds_read_b128 v[156:159], v232
	s_mov_b32 m0, s14
	v_mfma_f32_16x16x32_bf16 v[12:15], v[140:143], v[192:195], v[12:15]
	global_load_lds_dwordx4 v[196:197], off
	s_add_i32 m0, s14, 0x400
	v_mfma_f32_16x16x32_bf16 v[8:11], v[144:147], v[192:195], v[8:11]
	global_load_lds_dwordx4 v[198:199], off
	s_add_i32 m0, s14, 0x800
	v_mfma_f32_16x16x32_bf16 v[4:7], v[148:151], v[192:195], v[4:7]
	global_load_lds_dwordx4 v[200:201], off
	s_add_i32 m0, s14, 0xc00
	v_mfma_f32_16x16x32_bf16 v[0:3], v[152:155], v[192:195], v[0:3]
	ds_read_b128 v[188:191], v232 offset:1024
	global_load_lds_dwordx4 v[202:203], off
	s_mov_b32 m0, s98
	v_mfma_f32_16x16x32_bf16 v[76:79], v[140:143], v[208:211], v[76:79]
	global_load_lds_dwordx4 v[204:205], off
	s_add_i32 m0, s98, 0x400
	v_mfma_f32_16x16x32_bf16 v[80:83], v[144:147], v[208:211], v[80:83]
	global_load_lds_dwordx4 v[206:207], off
	v_mfma_f32_16x16x32_bf16 v[88:91], v[148:151], v[208:211], v[88:91]
	v_mfma_f32_16x16x32_bf16 v[92:95], v[152:155], v[208:211], v[92:95]
	ds_read_b128 v[192:195], v232 offset:2048
	s_add_i32 s12, s10, 1
	s_cmp_lg_u32 s10, 2
	s_cselect_b32 s10, s12, 0
	s_add_i32 s11, s11, 1
	s_mul_i32 s12, s10, 0x6000
	s_add_i32 s12, s12, 16
	s_add_i32 s13, s12, 0x6000
	s_cmp_eq_u32 s10, 2
	s_cselect_b32 s13, 16, s13
	s_min_u32 s14, s11, 28
	s_add_i32 s14, s14, 1
	s_lshl_b32 s96, s14, 6
	s_add_i32 s14, s12, s8
	s_add_i32 s98, s12, s9
	s_addk_i32 s98, 0x4000
	ds_read_b128 v[208:211], v232 offset:3072
	s_waitcnt lgkmcnt(3)
	v_mfma_f32_16x16x32_bf16 v[124:127], v[216:219], v[156:159], v[124:127]
	v_lshl_add_u64 v[234:235], v[130:131], 0, s[96:97]
	v_mfma_f32_16x16x32_bf16 v[120:123], v[220:223], v[156:159], v[120:123]
	v_lshl_add_u64 v[196:197], v[234:235], 0, s[62:63]
	v_mfma_f32_16x16x32_bf16 v[116:119], v[224:227], v[156:159], v[116:119]
	v_lshl_add_u64 v[198:199], v[234:235], 0, s[60:61]
	v_mfma_f32_16x16x32_bf16 v[112:115], v[228:231], v[156:159], v[112:115]
	ds_read_b128 v[156:159], v232 offset:4096
	s_waitcnt lgkmcnt(3)
	v_mfma_f32_16x16x32_bf16 v[108:111], v[216:219], v[188:191], v[108:111]
	v_lshl_add_u64 v[200:201], v[234:235], 0, s[16:17]
	v_mfma_f32_16x16x32_bf16 v[104:107], v[220:223], v[188:191], v[104:107]
	v_lshl_add_u64 v[202:203], v[234:235], 0, s[24:25]
	v_mfma_f32_16x16x32_bf16 v[100:103], v[224:227], v[188:191], v[100:103]
	v_lshl_add_u64 v[234:235], v[132:133], 0, s[96:97]
	v_mfma_f32_16x16x32_bf16 v[96:99], v[228:231], v[188:191], v[96:99]
	ds_read_b128 v[188:191], v232 offset:5120
	s_waitcnt lgkmcnt(3)
	v_mfma_f32_16x16x32_bf16 v[84:87], v[216:219], v[192:195], v[84:87]
	v_lshl_add_u64 v[204:205], v[234:235], 0, s[62:63]
	v_mfma_f32_16x16x32_bf16 v[72:75], v[220:223], v[192:195], v[72:75]
	v_lshl_add_u64 v[206:207], v[234:235], 0, s[60:61]
	v_mfma_f32_16x16x32_bf16 v[68:71], v[224:227], v[192:195], v[68:71]
	v_mfma_f32_16x16x32_bf16 v[64:67], v[228:231], v[192:195], v[64:67]
	ds_read_b128 v[192:195], v232 offset:6144
	s_waitcnt lgkmcnt(3)
	v_mfma_f32_16x16x32_bf16 v[60:63], v[216:219], v[208:211], v[60:63]
	v_mfma_f32_16x16x32_bf16 v[56:59], v[220:223], v[208:211], v[56:59]
	v_mfma_f32_16x16x32_bf16 v[52:55], v[224:227], v[208:211], v[52:55]
	v_mfma_f32_16x16x32_bf16 v[48:51], v[228:231], v[208:211], v[48:51]
	ds_read_b128 v[208:211], v232 offset:7168
	s_waitcnt lgkmcnt(3)
	v_mfma_f32_16x16x32_bf16 v[44:47], v[216:219], v[156:159], v[44:47]
	v_add3_u32 v232, s13, v137, v138
	v_mfma_f32_16x16x32_bf16 v[40:43], v[220:223], v[156:159], v[40:43]
	v_add3_u32 v233, s13, v139, v138
	v_mfma_f32_16x16x32_bf16 v[36:39], v[224:227], v[156:159], v[36:39]
	v_mfma_f32_16x16x32_bf16 v[32:35], v[228:231], v[156:159], v[32:35]
	s_waitcnt vmcnt(6)
	s_waitcnt lgkmcnt(0)
	s_barrier
	v_mfma_f32_16x16x32_bf16 v[28:31], v[216:219], v[188:191], v[28:31]
	ds_read_b128 v[140:143], v233 offset:16384
	v_mfma_f32_16x16x32_bf16 v[24:27], v[220:223], v[188:191], v[24:27]
	ds_read_b128 v[144:147], v233 offset:17408
	v_mfma_f32_16x16x32_bf16 v[20:23], v[224:227], v[188:191], v[20:23]
	ds_read_b128 v[148:151], v233 offset:18432
	v_mfma_f32_16x16x32_bf16 v[16:19], v[228:231], v[188:191], v[16:19]
	ds_read_b128 v[152:155], v233 offset:19456
	ds_read_b128 v[156:159], v232
	s_mov_b32 m0, s14
	v_mfma_f32_16x16x32_bf16 v[12:15], v[216:219], v[192:195], v[12:15]
	global_load_lds_dwordx4 v[196:197], off
	s_add_i32 m0, s14, 0x400
	v_mfma_f32_16x16x32_bf16 v[8:11], v[220:223], v[192:195], v[8:11]
	global_load_lds_dwordx4 v[198:199], off
	s_add_i32 m0, s14, 0x800
	v_mfma_f32_16x16x32_bf16 v[4:7], v[224:227], v[192:195], v[4:7]
	global_load_lds_dwordx4 v[200:201], off
	s_add_i32 m0, s14, 0xc00
	v_mfma_f32_16x16x32_bf16 v[0:3], v[228:231], v[192:195], v[0:3]
	ds_read_b128 v[188:191], v232 offset:1024
	global_load_lds_dwordx4 v[202:203], off
	s_mov_b32 m0, s98
	v_mfma_f32_16x16x32_bf16 v[76:79], v[216:219], v[208:211], v[76:79]
	global_load_lds_dwordx4 v[204:205], off
	s_add_i32 m0, s98, 0x400
	v_mfma_f32_16x16x32_bf16 v[80:83], v[220:223], v[208:211], v[80:83]
	global_load_lds_dwordx4 v[206:207], off
	v_mfma_f32_16x16x32_bf16 v[88:91], v[224:227], v[208:211], v[88:91]
	v_mfma_f32_16x16x32_bf16 v[92:95], v[228:231], v[208:211], v[92:95]
	ds_read_b128 v[192:195], v232 offset:2048
	s_add_i32 s12, s10, 1
	s_cmp_lg_u32 s10, 2
	s_cselect_b32 s10, s12, 0
	s_add_i32 s11, s11, 1
	s_cmp_eq_u32 s11, 32
	s_cbranch_scc0 .LBB1_56
	s_waitcnt lgkmcnt(0)
	s_setprio 0
	s_cmpk_lt_i32 s7, 0x80
	v_readlane_b32 s10, v242, 5
	s_waitcnt vmcnt(0)
	s_cselect_b64 s[8:9], -1, 0
	v_readlane_b32 s11, v242, 6
	s_and_b64 s[8:9], s[10:11], s[8:9]
	s_mov_b64 s[42:43], -1
	s_and_b64 vcc, exec, s[8:9]
	v_cvt_pk_bf16_f32 v124, v124, v125
	v_cvt_pk_bf16_f32 v125, v126, v127
	v_cvt_pk_bf16_f32 v120, v120, v121
	v_cvt_pk_bf16_f32 v121, v122, v123
	v_cvt_pk_bf16_f32 v116, v116, v117
	v_cvt_pk_bf16_f32 v117, v118, v119
	v_cvt_pk_bf16_f32 v112, v112, v113
	v_cvt_pk_bf16_f32 v113, v114, v115
	v_cvt_pk_bf16_f32 v108, v108, v109
	v_cvt_pk_bf16_f32 v109, v110, v111
	v_cvt_pk_bf16_f32 v104, v104, v105
	v_cvt_pk_bf16_f32 v105, v106, v107
	v_cvt_pk_bf16_f32 v100, v100, v101
	v_cvt_pk_bf16_f32 v101, v102, v103
	v_cvt_pk_bf16_f32 v96, v96, v97
	v_cvt_pk_bf16_f32 v97, v98, v99
	v_cvt_pk_bf16_f32 v84, v84, v85
	v_cvt_pk_bf16_f32 v85, v86, v87
	v_cvt_pk_bf16_f32 v72, v72, v73
	v_cvt_pk_bf16_f32 v73, v74, v75
	v_cvt_pk_bf16_f32 v68, v68, v69
	v_cvt_pk_bf16_f32 v69, v70, v71
	v_cvt_pk_bf16_f32 v64, v64, v65
	v_cvt_pk_bf16_f32 v65, v66, v67
	v_cvt_pk_bf16_f32 v60, v60, v61
	v_cvt_pk_bf16_f32 v61, v62, v63
	v_cvt_pk_bf16_f32 v56, v56, v57
	v_cvt_pk_bf16_f32 v57, v58, v59
	v_cvt_pk_bf16_f32 v52, v52, v53
	v_cvt_pk_bf16_f32 v53, v54, v55
	v_cvt_pk_bf16_f32 v48, v48, v49
	v_cvt_pk_bf16_f32 v49, v50, v51
	v_cvt_pk_bf16_f32 v44, v44, v45
	v_cvt_pk_bf16_f32 v45, v46, v47
	v_cvt_pk_bf16_f32 v40, v40, v41
	v_cvt_pk_bf16_f32 v41, v42, v43
	v_cvt_pk_bf16_f32 v36, v36, v37
	v_cvt_pk_bf16_f32 v37, v38, v39
	v_cvt_pk_bf16_f32 v32, v32, v33
	v_cvt_pk_bf16_f32 v33, v34, v35
	v_cvt_pk_bf16_f32 v28, v28, v29
	v_cvt_pk_bf16_f32 v29, v30, v31
	v_cvt_pk_bf16_f32 v24, v24, v25
	v_cvt_pk_bf16_f32 v25, v26, v27
	v_cvt_pk_bf16_f32 v20, v20, v21
	v_cvt_pk_bf16_f32 v21, v22, v23
	v_cvt_pk_bf16_f32 v16, v16, v17
	v_cvt_pk_bf16_f32 v17, v18, v19
	v_cvt_pk_bf16_f32 v12, v12, v13
	v_cvt_pk_bf16_f32 v13, v14, v15
	v_cvt_pk_bf16_f32 v14, v8, v9
	v_cvt_pk_bf16_f32 v15, v10, v11
	v_cvt_pk_bf16_f32 v8, v4, v5
	v_cvt_pk_bf16_f32 v9, v6, v7
	v_cvt_pk_bf16_f32 v10, v0, v1
	v_cvt_pk_bf16_f32 v11, v2, v3
	v_cvt_pk_bf16_f32 v2, v76, v77
	v_cvt_pk_bf16_f32 v3, v78, v79
	v_cvt_pk_bf16_f32 v6, v80, v81
	v_cvt_pk_bf16_f32 v7, v82, v83
	v_cvt_pk_bf16_f32 v0, v88, v89
	v_cvt_pk_bf16_f32 v1, v90, v91
	v_cvt_pk_bf16_f32 v4, v92, v93
	v_cvt_pk_bf16_f32 v5, v94, v95
	s_waitcnt vmcnt(0)
	s_barrier
	s_cbranch_vccnz .LBB1_59
	s_load_dwordx16 s[64:79], s[0:1], 0x140
	v_or_b32_e32 v18, s4, v135
	v_add_u32_e32 v18, s6, v18
	v_lshl_or_b32 v19, v136, 2, s40
	v_or_b32_e32 v22, s5, v19
	v_ashrrev_i32_e32 v19, 31, v18
	v_lshlrev_b64 v[26:27], 12, v[18:19]
	v_ashrrev_i32_e32 v23, 31, v22
	s_waitcnt lgkmcnt(0)
	v_lshl_add_u64 v[26:27], s[76:77], 0, v[26:27]
	v_lshlrev_b64 v[22:23], 1, v[22:23]
	v_lshl_add_u64 v[26:27], v[26:27], 0, v[22:23]
	global_store_dwordx2 v[26:27], v[124:125], off
	global_store_dwordx2 v[26:27], v[120:121], off offset:32
	global_store_dwordx2 v[26:27], v[116:117], off offset:64
	global_store_dwordx2 v[26:27], v[112:113], off offset:96
	v_or_b32_e32 v26, 16, v18
	v_ashrrev_i32_e32 v27, 31, v26
	v_lshlrev_b64 v[26:27], 12, v[26:27]
	v_lshl_add_u64 v[26:27], s[76:77], 0, v[26:27]
	v_lshl_add_u64 v[26:27], v[26:27], 0, v[22:23]
	global_store_dwordx2 v[26:27], v[108:109], off
	global_store_dwordx2 v[26:27], v[104:105], off offset:32
	global_store_dwordx2 v[26:27], v[100:101], off offset:64
	global_store_dwordx2 v[26:27], v[96:97], off offset:96
	v_or_b32_e32 v26, 32, v18
	v_ashrrev_i32_e32 v27, 31, v26
	v_lshlrev_b64 v[26:27], 12, v[26:27]
	v_lshl_add_u64 v[26:27], s[76:77], 0, v[26:27]
	v_lshl_add_u64 v[26:27], v[26:27], 0, v[22:23]
	global_store_dwordx2 v[26:27], v[84:85], off
	global_store_dwordx2 v[26:27], v[72:73], off offset:32
	global_store_dwordx2 v[26:27], v[68:69], off offset:64
	global_store_dwordx2 v[26:27], v[64:65], off offset:96
	v_or_b32_e32 v26, 48, v18
	v_ashrrev_i32_e32 v27, 31, v26
	v_lshlrev_b64 v[26:27], 12, v[26:27]
	v_lshl_add_u64 v[26:27], s[76:77], 0, v[26:27]
	v_lshl_add_u64 v[26:27], v[26:27], 0, v[22:23]
	global_store_dwordx2 v[26:27], v[60:61], off
	global_store_dwordx2 v[26:27], v[56:57], off offset:32
	global_store_dwordx2 v[26:27], v[52:53], off offset:64
	global_store_dwordx2 v[26:27], v[48:49], off offset:96
	v_or_b32_e32 v26, 64, v18
	v_ashrrev_i32_e32 v27, 31, v26
	v_lshlrev_b64 v[26:27], 12, v[26:27]
	v_lshl_add_u64 v[26:27], s[76:77], 0, v[26:27]
	v_lshl_add_u64 v[26:27], v[26:27], 0, v[22:23]
	global_store_dwordx2 v[26:27], v[44:45], off
	global_store_dwordx2 v[26:27], v[40:41], off offset:32
	global_store_dwordx2 v[26:27], v[36:37], off offset:64
	global_store_dwordx2 v[26:27], v[32:33], off offset:96
	v_or_b32_e32 v26, 0x50, v18
	v_ashrrev_i32_e32 v27, 31, v26
	v_lshlrev_b64 v[26:27], 12, v[26:27]
	v_lshl_add_u64 v[26:27], s[76:77], 0, v[26:27]
	v_lshl_add_u64 v[26:27], v[26:27], 0, v[22:23]
	global_store_dwordx2 v[26:27], v[28:29], off
	global_store_dwordx2 v[26:27], v[24:25], off offset:32
	global_store_dwordx2 v[26:27], v[20:21], off offset:64
	global_store_dwordx2 v[26:27], v[16:17], off offset:96
	v_or_b32_e32 v26, 0x60, v18
	v_ashrrev_i32_e32 v27, 31, v26
	v_lshlrev_b64 v[26:27], 12, v[26:27]
	v_lshl_add_u64 v[26:27], s[76:77], 0, v[26:27]
	v_or_b32_e32 v18, 0x70, v18
	v_lshl_add_u64 v[26:27], v[26:27], 0, v[22:23]
	v_ashrrev_i32_e32 v19, 31, v18
	global_store_dwordx2 v[26:27], v[12:13], off
	global_store_dwordx2 v[26:27], v[14:15], off offset:32
	global_store_dwordx2 v[26:27], v[8:9], off offset:64
	global_store_dwordx2 v[26:27], v[10:11], off offset:96
	v_lshlrev_b64 v[18:19], 12, v[18:19]
	v_lshl_add_u64 v[18:19], s[76:77], 0, v[18:19]
	s_load_dwordx16 s[64:79], s[0:1], 0x100
	v_lshl_add_u64 v[18:19], v[18:19], 0, v[22:23]
	s_mov_b64 s[42:43], 0
	global_store_dwordx2 v[18:19], v[2:3], off
	global_store_dwordx2 v[18:19], v[6:7], off offset:32
	global_store_dwordx2 v[18:19], v[0:1], off offset:64
	global_store_dwordx2 v[18:19], v[4:5], off offset:96

.LBB1_1179:
	v_mov_b32_e32 v138, v162
	s_lshl_b32 s6, s5, 8
	v_readfirstlane_b32 s7, v138
	v_lshrrev_b32_e32 v0, 3, v138
	v_and_b32_e32 v0, 6, v0
	s_movk_i32 s11, 0x78
	s_and_b32 s9, s7, 0xffffffc0
	s_waitcnt lgkmcnt(0)
	v_bfe_u32 v2, v138, 2, 4
	v_lshrrev_b32_e64 v0, v0, s11
	s_add_i32 s9, s9, s6
	v_xor_b32_e32 v3, v0, v138
	v_or_b32_e32 v0, s9, v2
	v_ashrrev_i32_e32 v1, 31, v0
	v_lshlrev_b64 v[0:1], 11, v[0:1]
	v_lshlrev_b32_e32 v3, 4, v3
	s_lshl_b32 s30, s4, 7
	v_lshl_add_u64 v[0:1], s[74:75], 0, v[0:1]
	v_and_b32_e32 v128, 48, v3
	s_load_dwordx16 s[80:95], s[0:1], 0xc0
	s_ashr_i32 s8, s7, 6
	v_lshl_add_u64 v[130:131], v[0:1], 0, v[128:129]
	v_or_b32_e32 v0, s30, v2
	v_lshl_add_u32 v0, s8, 5, v0
	v_ashrrev_i32_e32 v1, 31, v0
	v_lshlrev_b64 v[0:1], 11, v[0:1]
	s_waitcnt lgkmcnt(0)
	v_lshl_add_u64 v[0:1], s[84:85], 0, v[0:1]
	v_lshl_add_u64 v[132:133], v[0:1], 0, v[128:129]
	v_lshrrev_b32_e32 v0, 1, v138
	v_and_b32_e32 v0, 6, v0
	v_bfe_u32 v140, v138, 4, 2
	s_lshl_b32 s9, s8, 12
	v_lshrrev_b32_e64 v0, v0, s11
	v_and_b32_e32 v139, 15, v138
	s_lshl_b32 s10, s8, 11
	s_and_b32 s8, s7, 0xffffff80
	v_bitop3_b32 v0, v0, v140, 3 bitop3:0x6c
	s_and_b32 s7, s7, 64
	s_add_i32 s11, s9, 16
	v_lshlrev_b32_e32 v134, 4, v0
	v_or_b32_e32 v0, s7, v139
	s_mov_b32 m0, s11
	v_lshlrev_b32_e32 v135, 6, v0
	s_barrier
	global_load_lds_dwordx4 v[130:131], off
	v_lshl_add_u64 v[0:1], v[130:131], 0, s[34:35]
	s_add_i32 m0, s11, 0x400
	s_mov_b64 s[12:13], 0x10000
	global_load_lds_dwordx4 v[0:1], off
	v_lshl_add_u64 v[0:1], v[130:131], 0, s[12:13]
	s_add_i32 m0, s11, 0x800
	s_mov_b64 s[12:13], 0x18000
	global_load_lds_dwordx4 v[0:1], off
	v_lshl_add_u64 v[0:1], v[130:131], 0, s[12:13]
	s_add_i32 m0, s11, 0xc00
	s_sub_i32 s12, s11, s10
	global_load_lds_dwordx4 v[0:1], off
	s_add_i32 m0, s12, 0x4000
	v_lshl_add_u64 v[0:1], v[132:133], 0, s[34:35]
	global_load_lds_dwordx4 v[132:133], off
	s_add_i32 m0, s12, 0x4400
	s_mov_b64 s[14:15], 0x8040
	global_load_lds_dwordx4 v[0:1], off
	v_lshl_add_u64 v[0:1], v[130:131], 0, 64
	s_add_i32 m0, s11, 0x6000
	s_mov_b64 s[16:17], 0x10040
	global_load_lds_dwordx4 v[0:1], off
	v_lshl_add_u64 v[0:1], v[130:131], 0, s[14:15]
	s_add_i32 m0, s11, 0x6400
	v_or_b32_e32 v141, s8, v139
	global_load_lds_dwordx4 v[0:1], off
	v_lshl_add_u64 v[0:1], v[130:131], 0, s[16:17]
	s_add_i32 m0, s11, 0x6800
	s_mov_b64 s[16:17], 0x18040
	global_load_lds_dwordx4 v[0:1], off
	v_lshl_add_u64 v[0:1], v[130:131], 0, s[16:17]
	s_add_i32 m0, s11, 0x6c00
	v_lshlrev_b32_e32 v128, 6, v141
	global_load_lds_dwordx4 v[0:1], off
	v_lshl_add_u64 v[0:1], v[132:133], 0, 64
	s_add_i32 m0, s12, 0xa000
	s_mov_b32 s11, 0
	global_load_lds_dwordx4 v[0:1], off
	v_lshl_add_u64 v[0:1], v[132:133], 0, s[14:15]
	s_add_i32 m0, s12, 0xa400
	s_mov_b32 s12, 0
	global_load_lds_dwordx4 v[0:1], off
	v_mov_b32_e32 v0, 0
	v_mov_b32_e32 v1, v0
	v_mov_b32_e32 v2, v0
	v_mov_b32_e32 v3, v0
	v_mov_b32_e32 v4, v0
	v_mov_b32_e32 v5, v0
	v_mov_b32_e32 v6, v0
	v_mov_b32_e32 v7, v0
	v_mov_b32_e32 v8, v0
	v_mov_b32_e32 v9, v0
	v_mov_b32_e32 v10, v0
	v_mov_b32_e32 v11, v0
	v_mov_b32_e32 v12, v0
	v_mov_b32_e32 v13, v0
	v_mov_b32_e32 v14, v0
	v_mov_b32_e32 v15, v0
	v_mov_b32_e32 v16, v0
	v_mov_b32_e32 v17, v0
	v_mov_b32_e32 v18, v0
	v_mov_b32_e32 v19, v0
	v_mov_b32_e32 v20, v0
	v_mov_b32_e32 v21, v0
	v_mov_b32_e32 v22, v0
	v_mov_b32_e32 v23, v0
	v_mov_b32_e32 v24, v0
	v_mov_b32_e32 v25, v0
	v_mov_b32_e32 v26, v0
	v_mov_b32_e32 v27, v0
	v_mov_b32_e32 v28, v0
	v_mov_b32_e32 v29, v0
	v_mov_b32_e32 v30, v0
	v_mov_b32_e32 v31, v0
	v_mov_b32_e32 v32, v0
	v_mov_b32_e32 v33, v0
	v_mov_b32_e32 v34, v0
	v_mov_b32_e32 v35, v0
	v_mov_b32_e32 v36, v0
	v_mov_b32_e32 v37, v0
	v_mov_b32_e32 v38, v0
	v_mov_b32_e32 v39, v0
	v_mov_b32_e32 v40, v0
	v_mov_b32_e32 v41, v0
	v_mov_b32_e32 v42, v0
	v_mov_b32_e32 v43, v0
	v_mov_b32_e32 v44, v0
	v_mov_b32_e32 v45, v0
	v_mov_b32_e32 v46, v0
	v_mov_b32_e32 v47, v0
	v_mov_b32_e32 v48, v0
	v_mov_b32_e32 v49, v0
	v_mov_b32_e32 v50, v0
	v_mov_b32_e32 v51, v0
	v_mov_b32_e32 v68, v0
	v_mov_b32_e32 v69, v0
	v_mov_b32_e32 v70, v0
	v_mov_b32_e32 v71, v0
	v_mov_b32_e32 v72, v0
	v_mov_b32_e32 v73, v0
	v_mov_b32_e32 v74, v0
	v_mov_b32_e32 v75, v0
	v_mov_b32_e32 v76, v0
	v_mov_b32_e32 v77, v0
	v_mov_b32_e32 v78, v0
	v_mov_b32_e32 v79, v0
	v_mov_b32_e32 v80, v0
	v_mov_b32_e32 v81, v0
	v_mov_b32_e32 v82, v0
	v_mov_b32_e32 v83, v0
	v_mov_b32_e32 v84, v0
	v_mov_b32_e32 v85, v0
	v_mov_b32_e32 v86, v0
	v_mov_b32_e32 v87, v0
	v_mov_b32_e32 v88, v0
	v_mov_b32_e32 v89, v0
	v_mov_b32_e32 v90, v0
	v_mov_b32_e32 v91, v0
	v_mov_b32_e32 v92, v0
	v_mov_b32_e32 v93, v0
	v_mov_b32_e32 v94, v0
	v_mov_b32_e32 v95, v0
	v_mov_b32_e32 v96, v0
	v_mov_b32_e32 v97, v0
	v_mov_b32_e32 v98, v0
	v_mov_b32_e32 v99, v0
	v_mov_b32_e32 v100, v0
	v_mov_b32_e32 v101, v0
	v_mov_b32_e32 v102, v0
	v_mov_b32_e32 v103, v0
	v_mov_b32_e32 v104, v0
	v_mov_b32_e32 v105, v0
	v_mov_b32_e32 v106, v0
	v_mov_b32_e32 v107, v0
	v_mov_b32_e32 v108, v0
	v_mov_b32_e32 v109, v0
	v_mov_b32_e32 v110, v0
	v_mov_b32_e32 v111, v0
	v_mov_b32_e32 v112, v0
	v_mov_b32_e32 v113, v0
	v_mov_b32_e32 v114, v0
	v_mov_b32_e32 v115, v0
	v_mov_b32_e32 v116, v0
	v_mov_b32_e32 v117, v0
	v_mov_b32_e32 v118, v0
	v_mov_b32_e32 v119, v0
	v_mov_b32_e32 v120, v0
	v_mov_b32_e32 v121, v0
	v_mov_b32_e32 v122, v0
	v_mov_b32_e32 v123, v0
	v_mov_b32_e32 v124, v0
	v_mov_b32_e32 v125, v0
	v_mov_b32_e32 v126, v0
	v_mov_b32_e32 v127, v0
	v_mov_b32_e32 v60, v0
	v_mov_b32_e32 v61, v0
	v_mov_b32_e32 v62, v0
	v_mov_b32_e32 v63, v0
	v_mov_b32_e32 v64, v0
	v_mov_b32_e32 v65, v0
	v_mov_b32_e32 v66, v0
	v_mov_b32_e32 v67, v0
	v_mov_b32_e32 v52, v0
	v_mov_b32_e32 v53, v0
	v_mov_b32_e32 v54, v0
	v_mov_b32_e32 v55, v0
	v_mov_b32_e32 v56, v0
	v_mov_b32_e32 v57, v0
	v_mov_b32_e32 v58, v0
	v_mov_b32_e32 v59, v0
	s_mov_b64 s[16:17], 0x10080
	v_lshl_add_u64 v[196:197], v[130:131], 0, s[62:63]
	v_lshl_add_u64 v[198:199], v[130:131], 0, s[60:61]
	v_lshl_add_u64 v[200:201], v[130:131], 0, s[16:17]
	v_lshl_add_u64 v[202:203], v[130:131], 0, s[24:25]
	v_lshl_add_u64 v[204:205], v[132:133], 0, s[62:63]
	v_lshl_add_u64 v[206:207], v[132:133], 0, s[60:61]
	s_add_i32 s15, s9, 0xc010
	s_add_i32 s98, s10, 0x10010
	s_mov_b32 m0, s15
	s_nop 0
	global_load_lds_dwordx4 v[196:197], off
	s_add_i32 m0, s15, 0x400
	s_nop 0
	global_load_lds_dwordx4 v[198:199], off
	s_add_i32 m0, s15, 0x800
	s_nop 0
	global_load_lds_dwordx4 v[200:201], off
	s_add_i32 m0, s15, 0xc00
	s_nop 0
	global_load_lds_dwordx4 v[202:203], off
	s_mov_b32 m0, s98
	s_nop 0
	global_load_lds_dwordx4 v[204:205], off
	s_add_i32 m0, s98, 0x400
	s_nop 0
	global_load_lds_dwordx4 v[206:207], off
	s_waitcnt vmcnt(12)
	s_barrier
	v_add3_u32 v233, 16, v135, v134
	v_add3_u32 v232, 16, v128, v134
	ds_read_b128 v[142:145], v233 offset:16384
	ds_read_b128 v[146:149], v233 offset:17408
	ds_read_b128 v[150:153], v233 offset:18432
	ds_read_b128 v[154:157], v233 offset:19456
	ds_read_b128 v[158:161], v232
	ds_read_b128 v[188:191], v232 offset:1024
	ds_read_b128 v[192:195], v232 offset:2048
	s_setprio 1
.LBB1_1180:
	s_mul_i32 s13, s11, 0x6000
	s_add_i32 s13, s13, 16
	s_add_i32 s14, s13, 0x6000
	s_cmp_eq_u32 s11, 2
	s_cselect_b32 s14, 16, s14
	s_min_u32 s15, s12, 28
	s_add_i32 s15, s15, 1
	s_lshl_b32 s96, s15, 6
	s_add_i32 s15, s13, s9
	s_add_i32 s98, s13, s10
	s_addk_i32 s98, 0x4000
	ds_read_b128 v[208:211], v232 offset:3072
	s_waitcnt lgkmcnt(3)
	v_mfma_f32_16x16x32_bf16 v[124:127], v[142:145], v[158:161], v[124:127]
	v_lshl_add_u64 v[234:235], v[130:131], 0, s[96:97]
	v_mfma_f32_16x16x32_bf16 v[120:123], v[146:149], v[158:161], v[120:123]
	v_lshl_add_u64 v[196:197], v[234:235], 0, s[62:63]
	v_mfma_f32_16x16x32_bf16 v[116:119], v[150:153], v[158:161], v[116:119]
	v_lshl_add_u64 v[198:199], v[234:235], 0, s[60:61]
	v_mfma_f32_16x16x32_bf16 v[112:115], v[154:157], v[158:161], v[112:115]
	ds_read_b128 v[158:161], v232 offset:4096
	s_waitcnt lgkmcnt(3)
	v_mfma_f32_16x16x32_bf16 v[108:111], v[142:145], v[188:191], v[108:111]
	v_lshl_add_u64 v[200:201], v[234:235], 0, s[16:17]
	v_mfma_f32_16x16x32_bf16 v[104:107], v[146:149], v[188:191], v[104:107]
	v_lshl_add_u64 v[202:203], v[234:235], 0, s[24:25]
	v_mfma_f32_16x16x32_bf16 v[100:103], v[150:153], v[188:191], v[100:103]
	v_lshl_add_u64 v[234:235], v[132:133], 0, s[96:97]
	v_mfma_f32_16x16x32_bf16 v[96:99], v[154:157], v[188:191], v[96:99]
	ds_read_b128 v[188:191], v232 offset:5120
	s_waitcnt lgkmcnt(3)
	v_mfma_f32_16x16x32_bf16 v[92:95], v[142:145], v[192:195], v[92:95]
	v_lshl_add_u64 v[204:205], v[234:235], 0, s[62:63]
	v_mfma_f32_16x16x32_bf16 v[88:91], v[146:149], v[192:195], v[88:91]
	v_lshl_add_u64 v[206:207], v[234:235], 0, s[60:61]
	v_mfma_f32_16x16x32_bf16 v[84:87], v[150:153], v[192:195], v[84:87]
	v_mfma_f32_16x16x32_bf16 v[80:83], v[154:157], v[192:195], v[80:83]
	ds_read_b128 v[192:195], v232 offset:6144
	s_waitcnt lgkmcnt(3)
	v_mfma_f32_16x16x32_bf16 v[76:79], v[142:145], v[208:211], v[76:79]
	v_mfma_f32_16x16x32_bf16 v[72:75], v[146:149], v[208:211], v[72:75]
	v_mfma_f32_16x16x32_bf16 v[68:71], v[150:153], v[208:211], v[68:71]
	v_mfma_f32_16x16x32_bf16 v[48:51], v[154:157], v[208:211], v[48:51]
	ds_read_b128 v[208:211], v232 offset:7168
	s_waitcnt lgkmcnt(3)
	v_mfma_f32_16x16x32_bf16 v[44:47], v[142:145], v[158:161], v[44:47]
	v_add3_u32 v232, s14, v128, v134
	v_mfma_f32_16x16x32_bf16 v[40:43], v[146:149], v[158:161], v[40:43]
	v_add3_u32 v233, s14, v135, v134
	v_mfma_f32_16x16x32_bf16 v[36:39], v[150:153], v[158:161], v[36:39]
	v_mfma_f32_16x16x32_bf16 v[32:35], v[154:157], v[158:161], v[32:35]
	s_waitcnt vmcnt(6)
	s_waitcnt lgkmcnt(0)
	s_barrier
	v_mfma_f32_16x16x32_bf16 v[28:31], v[142:145], v[188:191], v[28:31]
	ds_read_b128 v[216:219], v233 offset:16384
	v_mfma_f32_16x16x32_bf16 v[24:27], v[146:149], v[188:191], v[24:27]
	ds_read_b128 v[220:223], v233 offset:17408
	v_mfma_f32_16x16x32_bf16 v[20:23], v[150:153], v[188:191], v[20:23]
	ds_read_b128 v[224:227], v233 offset:18432
	v_mfma_f32_16x16x32_bf16 v[16:19], v[154:157], v[188:191], v[16:19]
	ds_read_b128 v[228:231], v233 offset:19456
	ds_read_b128 v[158:161], v232
	s_mov_b32 m0, s15
	v_mfma_f32_16x16x32_bf16 v[12:15], v[142:145], v[192:195], v[12:15]
	global_load_lds_dwordx4 v[196:197], off
	s_add_i32 m0, s15, 0x400
	v_mfma_f32_16x16x32_bf16 v[8:11], v[146:149], v[192:195], v[8:11]
	global_load_lds_dwordx4 v[198:199], off
	s_add_i32 m0, s15, 0x800
	v_mfma_f32_16x16x32_bf16 v[4:7], v[150:153], v[192:195], v[4:7]
	global_load_lds_dwordx4 v[200:201], off
	s_add_i32 m0, s15, 0xc00
	v_mfma_f32_16x16x32_bf16 v[0:3], v[154:157], v[192:195], v[0:3]
	ds_read_b128 v[188:191], v232 offset:1024
	global_load_lds_dwordx4 v[202:203], off
	s_mov_b32 m0, s98
	v_mfma_f32_16x16x32_bf16 v[60:63], v[142:145], v[208:211], v[60:63]
	global_load_lds_dwordx4 v[204:205], off
	s_add_i32 m0, s98, 0x400
	v_mfma_f32_16x16x32_bf16 v[64:67], v[146:149], v[208:211], v[64:67]
	global_load_lds_dwordx4 v[206:207], off
	v_mfma_f32_16x16x32_bf16 v[52:55], v[150:153], v[208:211], v[52:55]
	v_mfma_f32_16x16x32_bf16 v[56:59], v[154:157], v[208:211], v[56:59]
	ds_read_b128 v[192:195], v232 offset:2048
	s_add_i32 s13, s11, 1
	s_cmp_lg_u32 s11, 2
	s_cselect_b32 s11, s13, 0
	s_add_i32 s12, s12, 1
	s_mul_i32 s13, s11, 0x6000
	s_add_i32 s13, s13, 16
	s_add_i32 s14, s13, 0x6000
	s_cmp_eq_u32 s11, 2
	s_cselect_b32 s14, 16, s14
	s_min_u32 s15, s12, 28
	s_add_i32 s15, s15, 1
	s_lshl_b32 s96, s15, 6
	s_add_i32 s15, s13, s9
	s_add_i32 s98, s13, s10
	s_addk_i32 s98, 0x4000
	ds_read_b128 v[208:211], v232 offset:3072
	s_waitcnt lgkmcnt(3)
	v_mfma_f32_16x16x32_bf16 v[124:127], v[216:219], v[158:161], v[124:127]
	v_lshl_add_u64 v[234:235], v[130:131], 0, s[96:97]
	v_mfma_f32_16x16x32_bf16 v[120:123], v[220:223], v[158:161], v[120:123]
	v_lshl_add_u64 v[196:197], v[234:235], 0, s[62:63]
	v_mfma_f32_16x16x32_bf16 v[116:119], v[224:227], v[158:161], v[116:119]
	v_lshl_add_u64 v[198:199], v[234:235], 0, s[60:61]
	v_mfma_f32_16x16x32_bf16 v[112:115], v[228:231], v[158:161], v[112:115]
	ds_read_b128 v[158:161], v232 offset:4096
	s_waitcnt lgkmcnt(3)
	v_mfma_f32_16x16x32_bf16 v[108:111], v[216:219], v[188:191], v[108:111]
	v_lshl_add_u64 v[200:201], v[234:235], 0, s[16:17]
	v_mfma_f32_16x16x32_bf16 v[104:107], v[220:223], v[188:191], v[104:107]
	v_lshl_add_u64 v[202:203], v[234:235], 0, s[24:25]
	v_mfma_f32_16x16x32_bf16 v[100:103], v[224:227], v[188:191], v[100:103]
	v_lshl_add_u64 v[234:235], v[132:133], 0, s[96:97]
	v_mfma_f32_16x16x32_bf16 v[96:99], v[228:231], v[188:191], v[96:99]
	ds_read_b128 v[188:191], v232 offset:5120
	s_waitcnt lgkmcnt(3)
	v_mfma_f32_16x16x32_bf16 v[92:95], v[216:219], v[192:195], v[92:95]
	v_lshl_add_u64 v[204:205], v[234:235], 0, s[62:63]
	v_mfma_f32_16x16x32_bf16 v[88:91], v[220:223], v[192:195], v[88:91]
	v_lshl_add_u64 v[206:207], v[234:235], 0, s[60:61]
	v_mfma_f32_16x16x32_bf16 v[84:87], v[224:227], v[192:195], v[84:87]
	v_mfma_f32_16x16x32_bf16 v[80:83], v[228:231], v[192:195], v[80:83]
	ds_read_b128 v[192:195], v232 offset:6144
	s_waitcnt lgkmcnt(3)
	v_mfma_f32_16x16x32_bf16 v[76:79], v[216:219], v[208:211], v[76:79]
	v_mfma_f32_16x16x32_bf16 v[72:75], v[220:223], v[208:211], v[72:75]
	v_mfma_f32_16x16x32_bf16 v[68:71], v[224:227], v[208:211], v[68:71]
	v_mfma_f32_16x16x32_bf16 v[48:51], v[228:231], v[208:211], v[48:51]
	ds_read_b128 v[208:211], v232 offset:7168
	s_waitcnt lgkmcnt(3)
	v_mfma_f32_16x16x32_bf16 v[44:47], v[216:219], v[158:161], v[44:47]
	v_add3_u32 v232, s14, v128, v134
	v_mfma_f32_16x16x32_bf16 v[40:43], v[220:223], v[158:161], v[40:43]
	v_add3_u32 v233, s14, v135, v134
	v_mfma_f32_16x16x32_bf16 v[36:39], v[224:227], v[158:161], v[36:39]
	v_mfma_f32_16x16x32_bf16 v[32:35], v[228:231], v[158:161], v[32:35]
	s_waitcnt vmcnt(6)
	s_waitcnt lgkmcnt(0)
	s_barrier
	v_mfma_f32_16x16x32_bf16 v[28:31], v[216:219], v[188:191], v[28:31]
	ds_read_b128 v[142:145], v233 offset:16384
	v_mfma_f32_16x16x32_bf16 v[24:27], v[220:223], v[188:191], v[24:27]
	ds_read_b128 v[146:149], v233 offset:17408
	v_mfma_f32_16x16x32_bf16 v[20:23], v[224:227], v[188:191], v[20:23]
	ds_read_b128 v[150:153], v233 offset:18432
	v_mfma_f32_16x16x32_bf16 v[16:19], v[228:231], v[188:191], v[16:19]
	ds_read_b128 v[154:157], v233 offset:19456
	ds_read_b128 v[158:161], v232
	s_mov_b32 m0, s15
	v_mfma_f32_16x16x32_bf16 v[12:15], v[216:219], v[192:195], v[12:15]
	global_load_lds_dwordx4 v[196:197], off
	s_add_i32 m0, s15, 0x400
	v_mfma_f32_16x16x32_bf16 v[8:11], v[220:223], v[192:195], v[8:11]
	global_load_lds_dwordx4 v[198:199], off
	s_add_i32 m0, s15, 0x800
	v_mfma_f32_16x16x32_bf16 v[4:7], v[224:227], v[192:195], v[4:7]
	global_load_lds_dwordx4 v[200:201], off
	s_add_i32 m0, s15, 0xc00
	v_mfma_f32_16x16x32_bf16 v[0:3], v[228:231], v[192:195], v[0:3]
	ds_read_b128 v[188:191], v232 offset:1024
	global_load_lds_dwordx4 v[202:203], off
	s_mov_b32 m0, s98
	v_mfma_f32_16x16x32_bf16 v[60:63], v[216:219], v[208:211], v[60:63]
	global_load_lds_dwordx4 v[204:205], off
	s_add_i32 m0, s98, 0x400
	v_mfma_f32_16x16x32_bf16 v[64:67], v[220:223], v[208:211], v[64:67]
	global_load_lds_dwordx4 v[206:207], off
	v_mfma_f32_16x16x32_bf16 v[52:55], v[224:227], v[208:211], v[52:55]
	v_mfma_f32_16x16x32_bf16 v[56:59], v[228:231], v[208:211], v[56:59]
	ds_read_b128 v[192:195], v232 offset:2048
	s_add_i32 s13, s11, 1
	s_cmp_lg_u32 s11, 2
	s_cselect_b32 s11, s13, 0
	s_add_i32 s12, s12, 1
	s_cmp_eq_u32 s12, 32
	s_cbranch_scc0 .LBB1_1180
	s_waitcnt lgkmcnt(0)
	s_setprio 0
	s_waitcnt vmcnt(0)
	s_waitcnt vmcnt(0)
	s_barrier
	s_load_dwordx8 s[80:87], s[0:1], 0x180
	s_cmp_lt_i32 s4, 64
	v_readlane_b32 s12, v242, 9
	s_cselect_b64 s[10:11], -1, 0
	v_readlane_b32 s13, v242, 10
	s_and_b64 s[10:11], s[12:13], s[10:11]
	s_mov_b64 s[38:39], -1
	s_and_b64 vcc, exec, s[10:11]
	s_movk_i32 s12, 0x2020
	s_cbranch_vccnz .LBB1_1291
	v_or_b32_e32 v128, s6, v139
	v_add_u32_e32 v132, s8, v128
	v_lshl_or_b32 v128, v140, 2, s30
	v_or_b32_e32 v130, s7, v128
	v_lshlrev_b32_e32 v134, 5, v132
	s_movk_i32 s8, 0x1fff
	v_ashrrev_i32_e32 v135, 31, v134
	v_cmp_lt_i32_e32 vcc, s8, v130
	s_and_saveexec_b64 s[8:9], vcc
	s_xor_b64 s[40:41], exec, s[8:9]
	s_cbranch_execz .LBB1_1186
	v_cmp_gt_u32_e64 s[38:39], s12, v130
	s_and_saveexec_b64 s[42:43], s[38:39]
	s_cbranch_execz .LBB1_1185
	v_add_u32_e32 v128, 0xffffe000, v130
	v_lshl_add_u64 v[136:137], v[134:135], 2, s[78:79]
	v_lshlrev_b64 v[142:143], 2, v[128:129]
	v_lshl_add_u64 v[136:137], v[136:137], 0, v[142:143]
	v_lshl_add_u64 v[142:143], s[22:23], 0, v[142:143]
	global_load_dwordx4 v[142:145], v[142:143], off
	s_waitcnt vmcnt(0)
	v_pk_add_f32 v[144:145], v[126:127], v[144:145]
	v_pk_add_f32 v[142:143], v[124:125], v[142:143]
	global_store_dwordx4 v[136:137], v[142:145], off
